# v61 + sample conv (P2): token raw rows loaded in one batch, no waits on the previous token stores
# baseline (speedup 1.0000x reference)
; __device__ __forceinline__ unsigned pk2(float lo, float hi) { f32x2_t v = {lo, hi}; bf16x2_t b = __builtin_convertvector(v, bf16x2_t); return __builtin_bit_cast(unsigned, b); }
; __device__ __forceinline__ float silu_f(float x) { return x * __builtin_amdgcn_rcpf(1.f + __builtin_amdgcn_exp2f(x * -1.4426950408889634f)); }
; template <bool SAMPLE, int NT>
; __device__ __forceinline__ void conv_run(const Params& p, int b, int row0, int t_first, int c) {
;     ...
;     auto getraw = [&](int t, float (&r)[8]) {
;         if (t >= 0) ld8f(proj + (size_t)(row0 + t) * NPROJ + 4096 + c, r);
;         else if (SAMPLE) ld8f32(p.state_conv + ((size_t)b * 3 + (3 + t)) * 2048 + c, r);
;         else {
; #pragma unroll
;             for (int j = 0; j < 8; ++j) r[j] = 0.f;
;         }
;     };
;     getraw(t_first - 3, r0); getraw(t_first - 2, r1); getraw(t_first - 1, r2);
; #pragma unroll
;     for (int i = 0; i < NT; ++i) {
;         const int t = t_first + i;
;         getraw(t, r3);
;         float o[8];
; #pragma unroll
;         for (int j = 0; j < 8; ++j) { const float v = cb[j] + w0[j] * r0[j] + w1[j] * r1[j] + w2[j] * r2[j] + w3[j] * r3[j]; o[j] = silu_f(v); }
;         uint4 ov; ov.x = pk2(o[0], o[1]); ov.y = pk2(o[2], o[3]); ov.z = pk2(o[4], o[5]); ov.w = pk2(o[6], o[7]);
;         *(uint4*)(xbc + (size_t)(row0 + t) * 2048 + c) = ov;
;         if (t >= T - 3) {
;             float* dst = p.out + (SAMPLE ? O_CS : O_CP) + ((size_t)b * 3 + (t - (T - 3))) * 2048 + c;
;             *(float4*)dst = make_float4(r3[0], r3[1], r3[2], r3[3]); *(float4*)(dst + 4) = make_float4(r3[4], r3[5], r3[6], r3[7]);
;         }
.LBB0_268:
	s_or_b64 exec, exec, s[38:39]
	v_lshl_add_u64 v[90:91], s[34:35], 0, v[90:91]
	v_lshl_add_u64 v[90:91], v[90:91], 0, v[64:65]
	v_add_co_u32_e32 v90, vcc, s48, v90
	s_waitcnt vmcnt(0)
	v_pk_fma_f32 v[52:53], v[32:33], v[52:53], v[36:37]
	v_addc_co_u32_e32 v91, vcc, 0, v91, vcc
	global_load_dwordx4 v[124:127], v[90:91], off
	s_mov_b64 s[54:55], 0x2000
	v_add_u32_e32 v142, s42, v93
	v_mul_lo_u32 v142, v142, s49
	v_mov_b32_e32 v143, v65
	v_lshl_add_u64 v[142:143], s[34:35], 0, v[142:143]
	v_lshl_add_u64 v[142:143], v[142:143], 0, v[64:65]
	v_lshl_add_u64 v[142:143], v[142:143], 0, s[54:55]
	global_load_dwordx4 v[144:147], v[142:143], off
	v_add_u32_e32 v142, s42, v95
	v_mul_lo_u32 v142, v142, s49
	v_mov_b32_e32 v143, v65
	v_lshl_add_u64 v[142:143], s[34:35], 0, v[142:143]
	v_lshl_add_u64 v[142:143], v[142:143], 0, v[64:65]
	v_lshl_add_u64 v[142:143], v[142:143], 0, s[54:55]
	global_load_dwordx4 v[148:151], v[142:143], off
	v_add_u32_e32 v142, s42, v97
	v_mul_lo_u32 v142, v142, s49
	v_mov_b32_e32 v143, v65
	v_lshl_add_u64 v[142:143], s[34:35], 0, v[142:143]
	v_lshl_add_u64 v[142:143], v[142:143], 0, v[64:65]
	v_lshl_add_u64 v[142:143], v[142:143], 0, s[54:55]
	global_load_dwordx4 v[152:155], v[142:143], off
	v_pk_fma_f32 v[54:55], v[34:35], v[54:55], v[38:39]
	v_pk_fma_f32 v[48:49], v[24:25], v[48:49], v[28:29]
	v_pk_fma_f32 v[50:51], v[26:27], v[50:51], v[30:31]
	v_pk_fma_f32 v[52:53], v[20:21], v[60:61], v[52:53]
	v_pk_fma_f32 v[54:55], v[22:23], v[62:63], v[54:55]
	v_pk_fma_f32 v[48:49], v[8:9], v[56:57], v[48:49]
	v_pk_fma_f32 v[50:51], v[10:11], v[58:59], v[50:51]
	v_pk_fma_f32 v[130:131], v[16:17], v[44:45], v[52:53]
	v_pk_fma_f32 v[132:133], v[18:19], v[46:47], v[54:55]
	v_pk_fma_f32 v[134:135], v[12:13], v[40:41], v[48:49]
	v_pk_fma_f32 v[136:137], v[14:15], v[42:43], v[50:51]
	v_lshlrev_b32_e32 v128, 12, v71
	v_lshl_add_u64 v[90:91], s[36:37], 0, v[64:65]
	v_mov_b32_e32 v129, v65
	v_lshl_add_u64 v[90:91], v[90:91], 0, s[22:23]
	s_mul_i32 s4, s43, 3
	v_lshl_add_u64 v[128:129], v[90:91], 0, v[128:129]
	s_waitcnt vmcnt(0)
	v_lshlrev_b32_e32 v52, 16, v124
	v_and_b32_e32 v53, 0xffff0000, v124
	v_lshlrev_b32_e32 v54, 16, v125
	v_and_b32_e32 v55, 0xffff0000, v125
	v_lshlrev_b32_e32 v48, 16, v126
	v_and_b32_e32 v49, 0xffff0000, v126
	v_lshlrev_b32_e32 v50, 16, v127
	v_and_b32_e32 v51, 0xffff0000, v127
	v_pk_fma_f32 v[124:125], v[4:5], v[52:53], v[130:131]
	v_pk_fma_f32 v[126:127], v[6:7], v[54:55], v[132:133]
	v_pk_fma_f32 v[130:131], v[0:1], v[48:49], v[134:135]
	v_pk_fma_f32 v[132:133], v[2:3], v[50:51], v[136:137]
	v_mul_f32_e32 v71, 0xbfb8aa3b, v124
	v_mul_f32_e32 v75, 0xbfb8aa3b, v125
	v_mul_f32_e32 v79, 0xbfb8aa3b, v126
	v_mul_f32_e32 v81, 0xbfb8aa3b, v127
	v_mul_f32_e32 v83, 0xbfb8aa3b, v130
	v_mul_f32_e32 v85, 0xbfb8aa3b, v131
	v_mul_f32_e32 v87, 0xbfb8aa3b, v132
	v_mul_f32_e32 v89, 0xbfb8aa3b, v133
	v_exp_f32_e32 v71, v71
	v_exp_f32_e32 v75, v75
	v_exp_f32_e32 v79, v79
	v_exp_f32_e32 v81, v81
	v_exp_f32_e32 v83, v83
	v_exp_f32_e32 v85, v85
	v_exp_f32_e32 v87, v87
	v_exp_f32_e32 v89, v89
	v_add_f32_e32 v71, 1.0, v71
	v_add_f32_e32 v75, 1.0, v75
	v_add_f32_e32 v79, 1.0, v79
	v_add_f32_e32 v81, 1.0, v81
	v_add_f32_e32 v83, 1.0, v83
	v_add_f32_e32 v85, 1.0, v85
	v_add_f32_e32 v87, 1.0, v87
	v_add_f32_e32 v89, 1.0, v89
	v_rcp_f32_e32 v134, v71
	v_rcp_f32_e32 v135, v75
	v_rcp_f32_e32 v136, v79
	v_rcp_f32_e32 v137, v81
	v_rcp_f32_e32 v138, v83
	v_rcp_f32_e32 v139, v85
	v_rcp_f32_e32 v140, v87
	v_rcp_f32_e32 v141, v89
	v_pk_mul_f32 v[124:125], v[124:125], v[134:135]
	v_pk_mul_f32 v[126:127], v[126:127], v[136:137]
	v_pk_mul_f32 v[130:131], v[130:131], v[138:139]
	v_pk_mul_f32 v[132:133], v[132:133], v[140:141]
	v_cvt_pk_bf16_f32 v124, v124, v125
	v_cvt_pk_bf16_f32 v125, v126, v127
	v_cvt_pk_bf16_f32 v126, v130, v131
	v_cvt_pk_bf16_f32 v127, v132, v133
	global_store_dwordx4 v[128:129], v[124:127], off
	s_and_saveexec_b64 s[36:37], s[8:9]
	s_cbranch_execz .LBB0_270
	s_load_dwordx2 s[38:39], s[0:1], 0xb0
	v_add_u32_e32 v124, s4, v92
	v_mov_b32_e32 v125, v65
	v_lshlrev_b64 v[124:125], 13, v[124:125]
	v_mov_b32_e32 v89, v65
	s_waitcnt lgkmcnt(0)
	v_lshl_add_u64 v[124:125], s[38:39], 0, v[124:125]
	v_lshl_add_u64 v[124:125], v[124:125], 0, v[88:89]
	v_lshl_add_u64 v[126:127], v[124:125], 0, s[24:25]
	v_add_co_u32_e32 v124, vcc, 0x9518000, v124
	s_nop 1
	v_addc_co_u32_e32 v125, vcc, 0, v125, vcc
	global_store_dwordx4 v[124:125], v[52:55], off
	global_store_dwordx4 v[126:127], v[48:51], off offset:16
; __device__ __forceinline__ unsigned pk2(float lo, float hi) { f32x2_t v = {lo, hi}; bf16x2_t b = __builtin_convertvector(v, bf16x2_t); return __builtin_bit_cast(unsigned, b); }
; __device__ __forceinline__ float silu_f(float x) { return x * __builtin_amdgcn_rcpf(1.f + __builtin_amdgcn_exp2f(x * -1.4426950408889634f)); }
; template <bool SAMPLE, int NT>
; __device__ __forceinline__ void conv_run(const Params& p, int b, int row0, int t_first, int c) {
;     ...
;     for (int i = 0; i < NT; ++i) {
;         const int t = t_first + i;
;         getraw(t, r3);
;         float o[8];
; #pragma unroll
;         for (int j = 0; j < 8; ++j) { const float v = cb[j] + w0[j] * r0[j] + w1[j] * r1[j] + w2[j] * r2[j] + w3[j] * r3[j]; o[j] = silu_f(v); }
;         uint4 ov; ov.x = pk2(o[0], o[1]); ov.y = pk2(o[2], o[3]); ov.z = pk2(o[4], o[5]); ov.w = pk2(o[6], o[7]);
;         *(uint4*)(xbc + (size_t)(row0 + t) * 2048 + c) = ov;
;         if (t >= T - 3) {
;             float* dst = p.out + (SAMPLE ? O_CS : O_CP) + ((size_t)b * 3 + (t - (T - 3))) * 2048 + c;
;             *(float4*)dst = make_float4(r3[0], r3[1], r3[2], r3[3]); *(float4*)(dst + 4) = make_float4(r3[4], r3[5], r3[6], r3[7]);
;         }
.LBB0_270:
	s_or_b64 exec, exec, s[36:37]
	v_add_u32_e32 v71, s42, v93
	v_mul_lo_u32 v124, v71, s49
	v_mov_b32_e32 v125, v65
	v_lshl_add_u64 v[124:125], s[34:35], 0, v[124:125]
	v_lshl_add_u64 v[124:125], v[124:125], 0, v[64:65]
	v_add_co_u32_e32 v124, vcc, 0x2000, v124
	v_pk_fma_f32 v[60:61], v[32:33], v[60:61], v[36:37]
	s_nop 0
	v_addc_co_u32_e32 v125, vcc, 0, v125, vcc
	v_mov_b64_e32 v[124:125], v[144:145]
	v_mov_b64_e32 v[126:127], v[146:147]
	v_pk_fma_f32 v[62:63], v[34:35], v[62:63], v[38:39]
	v_pk_fma_f32 v[56:57], v[24:25], v[56:57], v[28:29]
	v_pk_fma_f32 v[58:59], v[26:27], v[58:59], v[30:31]
	v_pk_fma_f32 v[60:61], v[20:21], v[44:45], v[60:61]
	v_pk_fma_f32 v[62:63], v[22:23], v[46:47], v[62:63]
	v_pk_fma_f32 v[56:57], v[8:9], v[40:41], v[56:57]
	v_pk_fma_f32 v[58:59], v[10:11], v[42:43], v[58:59]
	v_pk_fma_f32 v[130:131], v[16:17], v[52:53], v[60:61]
	v_pk_fma_f32 v[132:133], v[18:19], v[54:55], v[62:63]
	v_pk_fma_f32 v[134:135], v[12:13], v[48:49], v[56:57]
	v_pk_fma_f32 v[136:137], v[14:15], v[50:51], v[58:59]
	v_lshlrev_b32_e32 v128, 12, v71
	v_mov_b32_e32 v129, v65
	v_lshl_add_u64 v[128:129], v[90:91], 0, v[128:129]
	v_lshlrev_b32_e32 v56, 16, v124
	v_and_b32_e32 v57, 0xffff0000, v124
	v_lshlrev_b32_e32 v58, 16, v125
	v_and_b32_e32 v59, 0xffff0000, v125
	v_lshlrev_b32_e32 v60, 16, v126
	v_and_b32_e32 v61, 0xffff0000, v126
	v_lshlrev_b32_e32 v62, 16, v127
	v_and_b32_e32 v63, 0xffff0000, v127
	v_pk_fma_f32 v[124:125], v[4:5], v[56:57], v[130:131]
	v_pk_fma_f32 v[126:127], v[6:7], v[58:59], v[132:133]
	v_pk_fma_f32 v[130:131], v[0:1], v[60:61], v[134:135]
	v_pk_fma_f32 v[132:133], v[2:3], v[62:63], v[136:137]
	v_mul_f32_e32 v71, 0xbfb8aa3b, v124
	v_mul_f32_e32 v75, 0xbfb8aa3b, v125
	v_mul_f32_e32 v79, 0xbfb8aa3b, v126
	v_mul_f32_e32 v81, 0xbfb8aa3b, v127
	v_mul_f32_e32 v83, 0xbfb8aa3b, v130
	v_mul_f32_e32 v85, 0xbfb8aa3b, v131
	v_mul_f32_e32 v87, 0xbfb8aa3b, v132
	v_mul_f32_e32 v89, 0xbfb8aa3b, v133
	v_exp_f32_e32 v71, v71
	v_exp_f32_e32 v75, v75
	v_exp_f32_e32 v79, v79
	v_exp_f32_e32 v81, v81
	v_exp_f32_e32 v83, v83
	v_exp_f32_e32 v85, v85
	v_exp_f32_e32 v87, v87
	v_exp_f32_e32 v89, v89
	v_add_f32_e32 v71, 1.0, v71
	v_add_f32_e32 v75, 1.0, v75
	v_add_f32_e32 v79, 1.0, v79
	v_add_f32_e32 v81, 1.0, v81
	v_add_f32_e32 v83, 1.0, v83
	v_add_f32_e32 v85, 1.0, v85
	v_add_f32_e32 v87, 1.0, v87
	v_add_f32_e32 v89, 1.0, v89
	v_rcp_f32_e32 v134, v71
	v_rcp_f32_e32 v135, v75
	v_rcp_f32_e32 v136, v79
	v_rcp_f32_e32 v137, v81
	v_rcp_f32_e32 v138, v83
	v_rcp_f32_e32 v139, v85
	v_rcp_f32_e32 v140, v87
	v_rcp_f32_e32 v141, v89
	v_pk_mul_f32 v[124:125], v[124:125], v[134:135]
	v_pk_mul_f32 v[126:127], v[126:127], v[136:137]
	v_pk_mul_f32 v[130:131], v[130:131], v[138:139]
	v_pk_mul_f32 v[132:133], v[132:133], v[140:141]
	v_cvt_pk_bf16_f32 v124, v124, v125
	v_cvt_pk_bf16_f32 v125, v126, v127
	v_cvt_pk_bf16_f32 v126, v130, v131
	v_cvt_pk_bf16_f32 v127, v132, v133
	global_store_dwordx4 v[128:129], v[124:127], off
	s_and_saveexec_b64 s[36:37], s[10:11]
	s_cbranch_execz .LBB0_272
	s_load_dwordx2 s[38:39], s[0:1], 0xb0
	v_add_u32_e32 v124, s4, v94
	v_mov_b32_e32 v125, v65
	v_lshlrev_b64 v[124:125], 13, v[124:125]
	v_mov_b32_e32 v89, v65
	s_waitcnt lgkmcnt(0)
	v_lshl_add_u64 v[124:125], s[38:39], 0, v[124:125]
	v_lshl_add_u64 v[124:125], v[124:125], 0, v[88:89]
	v_lshl_add_u64 v[126:127], v[124:125], 0, s[24:25]
	v_add_co_u32_e32 v124, vcc, 0x9518000, v124
	s_nop 1
	v_addc_co_u32_e32 v125, vcc, 0, v125, vcc
	global_store_dwordx4 v[124:125], v[56:59], off
	global_store_dwordx4 v[126:127], v[60:63], off offset:16
; __device__ __forceinline__ unsigned pk2(float lo, float hi) { f32x2_t v = {lo, hi}; bf16x2_t b = __builtin_convertvector(v, bf16x2_t); return __builtin_bit_cast(unsigned, b); }
; __device__ __forceinline__ float silu_f(float x) { return x * __builtin_amdgcn_rcpf(1.f + __builtin_amdgcn_exp2f(x * -1.4426950408889634f)); }
; template <bool SAMPLE, int NT>
; __device__ __forceinline__ void conv_run(const Params& p, int b, int row0, int t_first, int c) {
;     ...
;     for (int i = 0; i < NT; ++i) {
;         const int t = t_first + i;
;         getraw(t, r3);
;         float o[8];
; #pragma unroll
;         for (int j = 0; j < 8; ++j) { const float v = cb[j] + w0[j] * r0[j] + w1[j] * r1[j] + w2[j] * r2[j] + w3[j] * r3[j]; o[j] = silu_f(v); }
;         uint4 ov; ov.x = pk2(o[0], o[1]); ov.y = pk2(o[2], o[3]); ov.z = pk2(o[4], o[5]); ov.w = pk2(o[6], o[7]);
;         *(uint4*)(xbc + (size_t)(row0 + t) * 2048 + c) = ov;
;         if (t >= T - 3) {
;             float* dst = p.out + (SAMPLE ? O_CS : O_CP) + ((size_t)b * 3 + (t - (T - 3))) * 2048 + c;
;             *(float4*)dst = make_float4(r3[0], r3[1], r3[2], r3[3]); *(float4*)(dst + 4) = make_float4(r3[4], r3[5], r3[6], r3[7]);
;         }
.LBB0_272:
	s_or_b64 exec, exec, s[36:37]
	v_add_u32_e32 v71, s42, v95
	v_mul_lo_u32 v124, v71, s49
	v_mov_b32_e32 v125, v65
	v_lshl_add_u64 v[124:125], s[34:35], 0, v[124:125]
	v_lshl_add_u64 v[124:125], v[124:125], 0, v[64:65]
	v_add_co_u32_e32 v124, vcc, 0x2000, v124
	v_pk_fma_f32 v[44:45], v[32:33], v[44:45], v[36:37]
	s_nop 0
	v_addc_co_u32_e32 v125, vcc, 0, v125, vcc
	v_mov_b64_e32 v[124:125], v[148:149]
	v_mov_b64_e32 v[126:127], v[150:151]
	v_pk_fma_f32 v[46:47], v[34:35], v[46:47], v[38:39]
	v_pk_fma_f32 v[40:41], v[24:25], v[40:41], v[28:29]
	v_pk_fma_f32 v[42:43], v[26:27], v[42:43], v[30:31]
	v_pk_fma_f32 v[44:45], v[20:21], v[52:53], v[44:45]
	v_pk_fma_f32 v[46:47], v[22:23], v[54:55], v[46:47]
	v_pk_fma_f32 v[40:41], v[8:9], v[48:49], v[40:41]
	v_pk_fma_f32 v[42:43], v[10:11], v[50:51], v[42:43]
	v_pk_fma_f32 v[130:131], v[16:17], v[56:57], v[44:45]
	v_pk_fma_f32 v[132:133], v[18:19], v[58:59], v[46:47]
	v_pk_fma_f32 v[134:135], v[12:13], v[60:61], v[40:41]
	v_pk_fma_f32 v[136:137], v[14:15], v[62:63], v[42:43]
	v_lshlrev_b32_e32 v128, 12, v71
	v_mov_b32_e32 v129, v65
	v_lshl_add_u64 v[128:129], v[90:91], 0, v[128:129]
	v_lshlrev_b32_e32 v40, 16, v124
	v_and_b32_e32 v41, 0xffff0000, v124
	v_lshlrev_b32_e32 v42, 16, v125
	v_and_b32_e32 v43, 0xffff0000, v125
	v_lshlrev_b32_e32 v44, 16, v126
	v_and_b32_e32 v45, 0xffff0000, v126
	v_lshlrev_b32_e32 v46, 16, v127
	v_and_b32_e32 v47, 0xffff0000, v127
	v_pk_fma_f32 v[124:125], v[4:5], v[40:41], v[130:131]
	v_pk_fma_f32 v[126:127], v[6:7], v[42:43], v[132:133]
	v_pk_fma_f32 v[130:131], v[0:1], v[44:45], v[134:135]
	v_pk_fma_f32 v[132:133], v[2:3], v[46:47], v[136:137]
	v_mul_f32_e32 v71, 0xbfb8aa3b, v124
	v_mul_f32_e32 v75, 0xbfb8aa3b, v125
	v_mul_f32_e32 v79, 0xbfb8aa3b, v126
	v_mul_f32_e32 v81, 0xbfb8aa3b, v127
	v_mul_f32_e32 v83, 0xbfb8aa3b, v130
	v_mul_f32_e32 v85, 0xbfb8aa3b, v131
	v_mul_f32_e32 v87, 0xbfb8aa3b, v132
	v_mul_f32_e32 v89, 0xbfb8aa3b, v133
	v_exp_f32_e32 v71, v71
	v_exp_f32_e32 v75, v75
	v_exp_f32_e32 v79, v79
	v_exp_f32_e32 v81, v81
	v_exp_f32_e32 v83, v83
	v_exp_f32_e32 v85, v85
	v_exp_f32_e32 v87, v87
	v_exp_f32_e32 v89, v89
	v_add_f32_e32 v71, 1.0, v71
	v_add_f32_e32 v75, 1.0, v75
	v_add_f32_e32 v79, 1.0, v79
	v_add_f32_e32 v81, 1.0, v81
	v_add_f32_e32 v83, 1.0, v83
	v_add_f32_e32 v85, 1.0, v85
	v_add_f32_e32 v87, 1.0, v87
	v_add_f32_e32 v89, 1.0, v89
	v_rcp_f32_e32 v134, v71
	v_rcp_f32_e32 v135, v75
	v_rcp_f32_e32 v136, v79
	v_rcp_f32_e32 v137, v81
	v_rcp_f32_e32 v138, v83
	v_rcp_f32_e32 v139, v85
	v_rcp_f32_e32 v140, v87
	v_rcp_f32_e32 v141, v89
	v_pk_mul_f32 v[124:125], v[124:125], v[134:135]
	v_pk_mul_f32 v[126:127], v[126:127], v[136:137]
	v_pk_mul_f32 v[130:131], v[130:131], v[138:139]
	v_pk_mul_f32 v[132:133], v[132:133], v[140:141]
	v_cvt_pk_bf16_f32 v124, v124, v125
	v_cvt_pk_bf16_f32 v125, v126, v127
	v_cvt_pk_bf16_f32 v126, v130, v131
	v_cvt_pk_bf16_f32 v127, v132, v133
	global_store_dwordx4 v[128:129], v[124:127], off
	s_and_saveexec_b64 s[36:37], s[6:7]
	s_cbranch_execz .LBB0_274
	s_load_dwordx2 s[38:39], s[0:1], 0xb0
	v_add_u32_e32 v124, s4, v96
	v_mov_b32_e32 v125, v65
	v_lshlrev_b64 v[124:125], 13, v[124:125]
	v_mov_b32_e32 v89, v65
	s_waitcnt lgkmcnt(0)
	v_lshl_add_u64 v[124:125], s[38:39], 0, v[124:125]
	v_lshl_add_u64 v[124:125], v[124:125], 0, v[88:89]
	v_lshl_add_u64 v[126:127], v[124:125], 0, s[24:25]
	v_add_co_u32_e32 v124, vcc, 0x9518000, v124
	s_nop 1
	v_addc_co_u32_e32 v125, vcc, 0, v125, vcc
	global_store_dwordx4 v[124:125], v[40:43], off
	global_store_dwordx4 v[126:127], v[44:47], off offset:16
.LBB0_274:
	s_or_b64 exec, exec, s[36:37]
	v_add_u32_e32 v71, s42, v97
	v_mul_lo_u32 v124, v71, s49
	v_mov_b32_e32 v125, v65
	v_lshl_add_u64 v[124:125], s[34:35], 0, v[124:125]
	v_lshl_add_u64 v[124:125], v[124:125], 0, v[64:65]
	v_add_co_u32_e32 v124, vcc, 0x2000, v124
	v_pk_fma_f32 v[32:33], v[32:33], v[52:53], v[36:37]
	s_nop 0
	v_addc_co_u32_e32 v125, vcc, 0, v125, vcc
	v_mov_b64_e32 v[124:125], v[152:153]
	v_mov_b64_e32 v[126:127], v[154:155]
	v_pk_fma_f32 v[34:35], v[34:35], v[54:55], v[38:39]
	v_pk_fma_f32 v[24:25], v[24:25], v[48:49], v[28:29]
	v_pk_fma_f32 v[26:27], v[26:27], v[50:51], v[30:31]
	v_pk_fma_f32 v[20:21], v[20:21], v[56:57], v[32:33]
	v_pk_fma_f32 v[22:23], v[22:23], v[58:59], v[34:35]
	v_pk_fma_f32 v[8:9], v[8:9], v[60:61], v[24:25]
	v_pk_fma_f32 v[10:11], v[10:11], v[62:63], v[26:27]
	v_pk_fma_f32 v[16:17], v[16:17], v[40:41], v[20:21]
	v_pk_fma_f32 v[18:19], v[18:19], v[42:43], v[22:23]
	v_pk_fma_f32 v[20:21], v[12:13], v[44:45], v[8:9]
	v_pk_fma_f32 v[22:23], v[14:15], v[46:47], v[10:11]
	v_lshlrev_b32_e32 v64, 12, v71
	v_lshlrev_b32_e32 v14, 16, v127
	v_lshlrev_b32_e32 v12, 16, v126
	v_lshlrev_b32_e32 v10, 16, v125
	v_lshlrev_b32_e32 v8, 16, v124
	v_and_b32_e32 v15, 0xffff0000, v127
	v_and_b32_e32 v13, 0xffff0000, v126
	v_and_b32_e32 v11, 0xffff0000, v125
	v_and_b32_e32 v9, 0xffff0000, v124
	v_pk_fma_f32 v[4:5], v[4:5], v[8:9], v[16:17]
	v_pk_fma_f32 v[6:7], v[6:7], v[10:11], v[18:19]
	v_pk_fma_f32 v[0:1], v[0:1], v[12:13], v[20:21]
	v_pk_fma_f32 v[2:3], v[2:3], v[14:15], v[22:23]
	v_mul_f32_e32 v16, 0xbfb8aa3b, v4
	v_mul_f32_e32 v17, 0xbfb8aa3b, v5
	v_mul_f32_e32 v18, 0xbfb8aa3b, v6
	v_mul_f32_e32 v19, 0xbfb8aa3b, v7
	v_mul_f32_e32 v20, 0xbfb8aa3b, v0
	v_mul_f32_e32 v21, 0xbfb8aa3b, v1
	v_mul_f32_e32 v22, 0xbfb8aa3b, v2
	v_mul_f32_e32 v23, 0xbfb8aa3b, v3
	v_exp_f32_e32 v16, v16
	v_exp_f32_e32 v17, v17
	v_exp_f32_e32 v18, v18
	v_exp_f32_e32 v19, v19
	v_exp_f32_e32 v20, v20
	v_exp_f32_e32 v21, v21
	v_exp_f32_e32 v22, v22
	v_exp_f32_e32 v23, v23
	v_add_f32_e32 v16, 1.0, v16
	v_add_f32_e32 v17, 1.0, v17
	v_add_f32_e32 v18, 1.0, v18
	v_add_f32_e32 v19, 1.0, v19
	v_add_f32_e32 v20, 1.0, v20
	v_add_f32_e32 v21, 1.0, v21
	v_add_f32_e32 v22, 1.0, v22
	v_add_f32_e32 v23, 1.0, v23
	v_rcp_f32_e32 v16, v16
	v_rcp_f32_e32 v17, v17
	v_rcp_f32_e32 v18, v18
	v_rcp_f32_e32 v19, v19
	v_rcp_f32_e32 v20, v20
	v_rcp_f32_e32 v21, v21
	v_rcp_f32_e32 v22, v22
	v_rcp_f32_e32 v23, v23
	v_pk_mul_f32 v[4:5], v[4:5], v[16:17]
	v_pk_mul_f32 v[6:7], v[6:7], v[18:19]
	v_pk_mul_f32 v[16:17], v[0:1], v[20:21]
	v_pk_mul_f32 v[18:19], v[2:3], v[22:23]
	v_cvt_pk_bf16_f32 v0, v4, v5
	v_cvt_pk_bf16_f32 v1, v6, v7
	v_cvt_pk_bf16_f32 v2, v16, v17
	v_cvt_pk_bf16_f32 v3, v18, v19
	v_lshl_add_u64 v[4:5], v[90:91], 0, v[64:65]
	global_store_dwordx4 v[4:5], v[0:3], off
	s_and_saveexec_b64 s[34:35], s[6:7]
	s_cbranch_execz .LBB0_276
	s_load_dwordx2 s[36:37], s[0:1], 0xb0
	v_add_u32_e32 v64, s4, v98
	v_lshlrev_b64 v[0:1], 13, v[64:65]
	v_mov_b32_e32 v89, v65
	s_waitcnt lgkmcnt(0)
	v_lshl_add_u64 v[0:1], s[36:37], 0, v[0:1]
	v_lshl_add_u64 v[0:1], v[0:1], 0, v[88:89]
	v_lshl_add_u64 v[2:3], v[0:1], 0, s[24:25]
	v_add_co_u32_e32 v0, vcc, 0x9518000, v0
	global_store_dwordx4 v[2:3], v[12:15], off offset:16
	s_nop 0
	v_addc_co_u32_e32 v1, vcc, 0, v1, vcc
	global_store_dwordx4 v[0:1], v[8:11], off
